# E22 + the same in-proj rs[] load hoisting applied to the diff layer (layer 2) in-projection epilogue
# speedup vs baseline: 1.0129x; 1.0049x over previous
; #define PG8_STAGE(bufoff, gbase, voff) do { _Pragma("unroll") for (int _i = 0; _i < 2; ++_i) \
;     __builtin_amdgcn_global_load_lds((const unsigned*)((const char*)(gbase) + (voff)[_i]), (LAS unsigned*)(lds + (bufoff) + ldsw + _i * 8192), 16, 0, 0); } while (0)
; #define PG8_LDA(dst, b, h) do { _Pragma("unroll") for (int m = 0; m < 4; ++m) _Pragma("unroll") for (int k = 0; k < 2; ++k) dst[m][k] = *(const LAS bf16x8*)(lds + PG8_SA(b, h) + aoff + m * 2048 + k * 1024); } while (0)
; #define PG8_LDB(dst, b, h) do { _Pragma("unroll") for (int n = 0; n < 2; ++n) _Pragma("unroll") for (int k = 0; k < 2; ++k) dst[n][k] = *(const LAS bf16x8*)(lds + PG8_SB(b, h) + boff + n * 2048 + k * 1024); } while (0)
; #define PG8_MMA(ai, bj, At, Bt) do { __builtin_amdgcn_s_setprio(1); _Pragma("unroll") for (int m = 0; m < 4; ++m) _Pragma("unroll") for (int n = 0; n < 2; ++n) _Pragma("unroll") for (int k = 0; k < 2; ++k) \
;     acc[ai][bj][m][n] = __builtin_amdgcn_mfma_f32_16x16x32_bf16(Bt[n][k], At[m][k], acc[ai][bj][m][n], 0, 0, 0); __builtin_amdgcn_s_setprio(0); } while (0)
; #define PG8_WAIT_V(n) asm volatile("s_waitcnt vmcnt(" #n ")" ::: "memory")
; #define PG8_WAIT_L(n) asm volatile("s_waitcnt lgkmcnt(" #n ")" ::: "memory")
; #define PG8_BAR __builtin_amdgcn_s_barrier()
; #define PG8_SCHED __builtin_amdgcn_sched_barrier(0)
; template <class Epi>
; DI void gemm_phase(LAS unsigned char* lds, const Gemm g, const StaticOrder& S, const Epi& E) {
;     ...
;       PG8_LDB(B0, 0, 0); PG8_SCHED; PG8_LDA(At, 0, 0); PG8_STAGE(PG8_SA(1, 1), a1 + hstep, voffA);
;       PG8_WAIT_L(8); PG8_BAR; PG8_WAIT_L(0); PG8_MMA(0, 0, At, B0); PG8_BAR; PG8_SCHED;
;       PG8_LDB(B1, 0, 1); PG8_STAGE(PG8_SB(0, 0), b2, voffB);
;       PG8_BAR; PG8_WAIT_L(0); PG8_MMA(0, 1, At, B1); PG8_BAR;
;       PG8_LDA(At, 0, 1); PG8_STAGE(PG8_SA(0, 0), a2, voffA);
;       PG8_BAR; PG8_WAIT_L(0); PG8_MMA(1, 0, At, B0); PG8_BAR; PG8_SCHED;
;       PG8_STAGE(PG8_SB(0, 1), b2 + hstep, voffB);
;       PG8_WAIT_V(6); PG8_BAR; PG8_MMA(1, 1, At, B1); PG8_BAR;
;       PG8_LDB(B0, 1, 0); PG8_SCHED; PG8_LDA(At, 1, 0); PG8_STAGE(PG8_SA(0, 1), a2 + hstep, voffA);
;       PG8_WAIT_L(8); PG8_BAR; PG8_WAIT_L(0); PG8_MMA(0, 0, At, B0); PG8_BAR; PG8_SCHED;
.LBB0_867:
	ds_read_b128 v[146:149], v163
	ds_read_b128 v[150:153], v163 offset:1024
	ds_read_b128 v[154:157], v163 offset:2048
	ds_read_b128 v[168:171], v163 offset:3072
	s_add_u32 s28, s14, 0xfff80080
	s_addc_u32 s29, s15, -1
	s_cmp_eq_u32 s66, 28
	s_cselect_b32 s31, s11, s29
	s_cselect_b32 s30, s13, s28
	s_cselect_b32 s29, s21, s65
	s_cselect_b32 s28, s23, s64
	v_lshl_add_u64 v[158:159], s[14:15], 0, v[140:141]
	s_add_i32 m0, s6, 0xc000
	ds_read_b128 v[172:175], v164
	ds_read_b128 v[176:179], v164 offset:1024
	ds_read_b128 v[180:183], v164 offset:2048
	ds_read_b128 v[184:187], v164 offset:3072
	ds_read_b128 v[188:191], v164 offset:4096
	ds_read_b128 v[192:195], v164 offset:5120
	ds_read_b128 v[196:199], v164 offset:6144
	ds_read_b128 v[200:203], v164 offset:7168
	global_load_lds_dwordx4 v[158:159], off
	v_lshl_add_u64 v[158:159], s[14:15], 0, v[138:139]
	s_add_i32 m0, s6, 0xe000
	s_nop 0
	global_load_lds_dwordx4 v[158:159], off
	s_waitcnt lgkmcnt(8)
	s_barrier
	s_waitcnt lgkmcnt(0)
	s_setprio 1
	s_waitcnt lgkmcnt(0)
	v_mfma_f32_16x16x32_bf16 v[124:127], v[146:149], v[172:175], v[124:127]
	v_mfma_f32_16x16x32_bf16 v[120:123], v[154:157], v[172:175], v[120:123]
	v_mfma_f32_16x16x32_bf16 v[108:111], v[146:149], v[180:183], v[108:111]
	v_mfma_f32_16x16x32_bf16 v[104:107], v[154:157], v[180:183], v[104:107]
	v_mfma_f32_16x16x32_bf16 v[92:95], v[146:149], v[188:191], v[92:95]
	v_mfma_f32_16x16x32_bf16 v[88:91], v[154:157], v[188:191], v[88:91]
	v_mfma_f32_16x16x32_bf16 v[76:79], v[146:149], v[196:199], v[76:79]
	v_mfma_f32_16x16x32_bf16 v[72:75], v[154:157], v[196:199], v[72:75]
	v_mfma_f32_16x16x32_bf16 v[124:127], v[150:153], v[176:179], v[124:127]
	v_mfma_f32_16x16x32_bf16 v[120:123], v[168:171], v[176:179], v[120:123]
	v_mfma_f32_16x16x32_bf16 v[108:111], v[150:153], v[184:187], v[108:111]
	v_mfma_f32_16x16x32_bf16 v[104:107], v[168:171], v[184:187], v[104:107]
	v_mfma_f32_16x16x32_bf16 v[92:95], v[150:153], v[192:195], v[92:95]
	v_mfma_f32_16x16x32_bf16 v[88:91], v[168:171], v[192:195], v[88:91]
	v_mfma_f32_16x16x32_bf16 v[76:79], v[150:153], v[200:203], v[76:79]
	v_mfma_f32_16x16x32_bf16 v[72:75], v[168:171], v[200:203], v[72:75]
	s_setprio 0
	s_barrier
	s_add_i32 s67, s42, s5
	v_lshl_add_u64 v[158:159], s[28:29], 0, v[130:131]
	s_mov_b32 m0, s67
	ds_read_b128 v[204:207], v165
	ds_read_b128 v[210:213], v165 offset:1024
	ds_read_b128 v[214:217], v165 offset:2048
	ds_read_b128 v[218:221], v165 offset:3072
	global_load_lds_dwordx4 v[158:159], off
	v_lshl_add_u64 v[222:223], s[28:29], 0, v[134:135]
	s_add_i32 m0, s67, 0x2000
	s_nop 0
	global_load_lds_dwordx4 v[222:223], off
	s_barrier
	s_waitcnt lgkmcnt(0)
	s_setprio 1
	s_waitcnt lgkmcnt(0)
	v_mfma_f32_16x16x32_bf16 v[116:119], v[204:207], v[172:175], v[116:119]
	v_mfma_f32_16x16x32_bf16 v[112:115], v[214:217], v[172:175], v[112:115]
	v_mfma_f32_16x16x32_bf16 v[100:103], v[204:207], v[180:183], v[100:103]
	v_mfma_f32_16x16x32_bf16 v[96:99], v[214:217], v[180:183], v[96:99]
	v_mfma_f32_16x16x32_bf16 v[84:87], v[204:207], v[188:191], v[84:87]
	v_mfma_f32_16x16x32_bf16 v[80:83], v[214:217], v[188:191], v[80:83]
	v_mfma_f32_16x16x32_bf16 v[68:71], v[204:207], v[196:199], v[68:71]
	v_mfma_f32_16x16x32_bf16 v[64:67], v[214:217], v[196:199], v[64:67]
	v_mfma_f32_16x16x32_bf16 v[116:119], v[210:213], v[176:179], v[116:119]
	v_mfma_f32_16x16x32_bf16 v[112:115], v[218:221], v[176:179], v[112:115]
	v_mfma_f32_16x16x32_bf16 v[100:103], v[210:213], v[184:187], v[100:103]
	v_mfma_f32_16x16x32_bf16 v[96:99], v[218:221], v[184:187], v[96:99]
	v_mfma_f32_16x16x32_bf16 v[84:87], v[210:213], v[192:195], v[84:87]
	v_mfma_f32_16x16x32_bf16 v[80:83], v[218:221], v[192:195], v[80:83]
	v_mfma_f32_16x16x32_bf16 v[68:71], v[210:213], v[200:203], v[68:71]
	v_mfma_f32_16x16x32_bf16 v[64:67], v[218:221], v[200:203], v[64:67]
	s_setprio 0
	s_mov_b32 m0, s6
	v_lshl_add_u64 v[224:225], s[30:31], 0, v[128:129]
	s_barrier
	ds_read_b128 v[172:175], v164 offset:16384
	ds_read_b128 v[176:179], v164 offset:17408
	ds_read_b128 v[180:183], v164 offset:18432
	ds_read_b128 v[184:187], v164 offset:19456
	ds_read_b128 v[188:191], v164 offset:20480
	ds_read_b128 v[192:195], v164 offset:21504
	ds_read_b128 v[196:199], v164 offset:22528
	ds_read_b128 v[200:203], v164 offset:23552
	global_load_lds_dwordx4 v[224:225], off
	v_lshl_add_u64 v[226:227], s[30:31], 0, v[132:133]
	s_mov_b32 m0, s7
	s_nop 0
	global_load_lds_dwordx4 v[226:227], off
	s_barrier
	s_waitcnt lgkmcnt(0)
	s_setprio 1
	s_waitcnt lgkmcnt(0)
	v_mfma_f32_16x16x32_bf16 v[60:63], v[146:149], v[172:175], v[60:63]
	v_mfma_f32_16x16x32_bf16 v[56:59], v[154:157], v[172:175], v[56:59]
	v_mfma_f32_16x16x32_bf16 v[44:47], v[146:149], v[180:183], v[44:47]
	v_mfma_f32_16x16x32_bf16 v[40:43], v[154:157], v[180:183], v[40:43]
	v_mfma_f32_16x16x32_bf16 v[28:31], v[146:149], v[188:191], v[28:31]
	v_mfma_f32_16x16x32_bf16 v[24:27], v[154:157], v[188:191], v[24:27]
	v_mfma_f32_16x16x32_bf16 v[12:15], v[146:149], v[196:199], v[12:15]
	v_mfma_f32_16x16x32_bf16 v[8:11], v[154:157], v[196:199], v[8:11]
	v_mfma_f32_16x16x32_bf16 v[60:63], v[150:153], v[176:179], v[60:63]
	v_mfma_f32_16x16x32_bf16 v[56:59], v[168:171], v[176:179], v[56:59]
	v_mfma_f32_16x16x32_bf16 v[44:47], v[150:153], v[184:187], v[44:47]
	v_mfma_f32_16x16x32_bf16 v[40:43], v[168:171], v[184:187], v[40:43]
	v_mfma_f32_16x16x32_bf16 v[28:31], v[150:153], v[192:195], v[28:31]
	v_mfma_f32_16x16x32_bf16 v[24:27], v[168:171], v[192:195], v[24:27]
	v_mfma_f32_16x16x32_bf16 v[12:15], v[150:153], v[200:203], v[12:15]
	v_mfma_f32_16x16x32_bf16 v[8:11], v[168:171], v[200:203], v[8:11]
	s_setprio 0
	s_barrier
; #define PG8_STAGE(bufoff, gbase, voff) do { _Pragma("unroll") for (int _i = 0; _i < 2; ++_i) \
;     __builtin_amdgcn_global_load_lds((const unsigned*)((const char*)(gbase) + (voff)[_i]), (LAS unsigned*)(lds + (bufoff) + ldsw + _i * 8192), 16, 0, 0); } while (0)
; #define PG8_LDA(dst, b, h) do { _Pragma("unroll") for (int m = 0; m < 4; ++m) _Pragma("unroll") for (int k = 0; k < 2; ++k) dst[m][k] = *(const LAS bf16x8*)(lds + PG8_SA(b, h) + aoff + m * 2048 + k * 1024); } while (0)
; #define PG8_LDB(dst, b, h) do { _Pragma("unroll") for (int n = 0; n < 2; ++n) _Pragma("unroll") for (int k = 0; k < 2; ++k) dst[n][k] = *(const LAS bf16x8*)(lds + PG8_SB(b, h) + boff + n * 2048 + k * 1024); } while (0)
; #define PG8_MMA(ai, bj, At, Bt) do { __builtin_amdgcn_s_setprio(1); _Pragma("unroll") for (int m = 0; m < 4; ++m) _Pragma("unroll") for (int n = 0; n < 2; ++n) _Pragma("unroll") for (int k = 0; k < 2; ++k) \
;     acc[ai][bj][m][n] = __builtin_amdgcn_mfma_f32_16x16x32_bf16(Bt[n][k], At[m][k], acc[ai][bj][m][n], 0, 0, 0); __builtin_amdgcn_s_setprio(0); } while (0)
; #define PG8_WAIT_V(n) asm volatile("s_waitcnt vmcnt(" #n ")" ::: "memory")
; #define PG8_WAIT_L(n) asm volatile("s_waitcnt lgkmcnt(" #n ")" ::: "memory")
; #define PG8_BAR __builtin_amdgcn_s_barrier()
; #define PG8_SCHED __builtin_amdgcn_sched_barrier(0)
; template <class Epi>
; DI void gemm_phase(LAS unsigned char* lds, const Gemm g, const StaticOrder& S, const Epi& E) {
;     ...
;       PG8_STAGE(PG8_SB(0, 1), b2 + hstep, voffB);
;       PG8_WAIT_V(6); PG8_BAR; PG8_MMA(1, 1, At, B1); PG8_BAR;
;       PG8_LDB(B0, 1, 0); PG8_SCHED; PG8_LDA(At, 1, 0); PG8_STAGE(PG8_SA(0, 1), a2 + hstep, voffA);
;       PG8_WAIT_L(8); PG8_BAR; PG8_WAIT_L(0); PG8_MMA(0, 0, At, B0); PG8_BAR; PG8_SCHED;
;       PG8_LDB(B1, 1, 1); PG8_STAGE(PG8_SB(1, 0), b3, voffB);
;       PG8_BAR; PG8_WAIT_L(0); PG8_MMA(0, 1, At, B1); PG8_BAR;
;       PG8_LDA(At, 1, 1); PG8_STAGE(PG8_SA(1, 0), a3, voffA);
;       PG8_BAR; PG8_WAIT_L(0); PG8_MMA(1, 0, At, B0); PG8_BAR; PG8_SCHED;
	s_add_u32 s68, s28, 0x80000
	s_addc_u32 s69, s29, 0
	s_add_i32 s67, s43, s5
	v_lshl_add_u64 v[146:147], s[68:69], 0, v[130:131]
	s_mov_b32 m0, s67
	s_nop 0
	global_load_lds_dwordx4 v[146:147], off
	v_lshl_add_u64 v[146:147], s[68:69], 0, v[134:135]
	s_add_i32 m0, s67, 0x2000
	s_nop 0
	global_load_lds_dwordx4 v[146:147], off
	s_waitcnt vmcnt(6)
	s_barrier
	s_setprio 1
	v_mfma_f32_16x16x32_bf16 v[52:55], v[204:207], v[172:175], v[52:55]
	v_mfma_f32_16x16x32_bf16 v[48:51], v[214:217], v[172:175], v[48:51]
	v_mfma_f32_16x16x32_bf16 v[36:39], v[204:207], v[180:183], v[36:39]
	v_mfma_f32_16x16x32_bf16 v[32:35], v[214:217], v[180:183], v[32:35]
	v_mfma_f32_16x16x32_bf16 v[20:23], v[204:207], v[188:191], v[20:23]
	v_mfma_f32_16x16x32_bf16 v[16:19], v[214:217], v[188:191], v[16:19]
	v_mfma_f32_16x16x32_bf16 v[4:7], v[204:207], v[196:199], v[4:7]
	v_mfma_f32_16x16x32_bf16 v[0:3], v[214:217], v[196:199], v[0:3]
	v_mfma_f32_16x16x32_bf16 v[52:55], v[210:213], v[176:179], v[52:55]
	v_mfma_f32_16x16x32_bf16 v[48:51], v[218:221], v[176:179], v[48:51]
	v_mfma_f32_16x16x32_bf16 v[36:39], v[210:213], v[184:187], v[36:39]
	v_mfma_f32_16x16x32_bf16 v[32:35], v[218:221], v[184:187], v[32:35]
	v_mfma_f32_16x16x32_bf16 v[20:23], v[210:213], v[192:195], v[20:23]
	v_mfma_f32_16x16x32_bf16 v[16:19], v[218:221], v[192:195], v[16:19]
	v_mfma_f32_16x16x32_bf16 v[4:7], v[210:213], v[200:203], v[4:7]
	v_mfma_f32_16x16x32_bf16 v[0:3], v[218:221], v[200:203], v[0:3]
	s_setprio 0
	s_add_i32 s67, 0, 0x18000
	v_add_u32_e32 v136, s67, v161
	s_barrier
	ds_read_b128 v[146:149], v136
	ds_read_b128 v[150:153], v136 offset:1024
	ds_read_b128 v[154:157], v136 offset:2048
	ds_read_b128 v[168:171], v136 offset:3072
	s_add_u32 s30, s30, 0x80000
	s_addc_u32 s31, s31, 0
	s_mov_b32 m0, s33
	v_lshl_add_u64 v[204:205], s[30:31], 0, v[128:129]
	ds_read_b128 v[172:175], v164 offset:32768
	ds_read_b128 v[176:179], v164 offset:33792
	ds_read_b128 v[180:183], v164 offset:34816
	ds_read_b128 v[184:187], v164 offset:35840
	ds_read_b128 v[188:191], v164 offset:36864
	ds_read_b128 v[192:195], v164 offset:37888
	ds_read_b128 v[196:199], v164 offset:38912
	ds_read_b128 v[200:203], v164 offset:39936
	global_load_lds_dwordx4 v[204:205], off
	v_lshl_add_u64 v[204:205], s[30:31], 0, v[132:133]
	s_mov_b32 m0, s34
	s_nop 0
	global_load_lds_dwordx4 v[204:205], off
	s_waitcnt lgkmcnt(8)
	s_barrier
	s_waitcnt lgkmcnt(0)
	s_setprio 1
	s_waitcnt lgkmcnt(0)
	v_mfma_f32_16x16x32_bf16 v[124:127], v[146:149], v[172:175], v[124:127]
	v_mfma_f32_16x16x32_bf16 v[120:123], v[154:157], v[172:175], v[120:123]
	v_mfma_f32_16x16x32_bf16 v[108:111], v[146:149], v[180:183], v[108:111]
	v_mfma_f32_16x16x32_bf16 v[104:107], v[154:157], v[180:183], v[104:107]
	v_mfma_f32_16x16x32_bf16 v[92:95], v[146:149], v[188:191], v[92:95]
	v_mfma_f32_16x16x32_bf16 v[88:91], v[154:157], v[188:191], v[88:91]
	v_mfma_f32_16x16x32_bf16 v[76:79], v[146:149], v[196:199], v[76:79]
	v_mfma_f32_16x16x32_bf16 v[72:75], v[154:157], v[196:199], v[72:75]
	v_mfma_f32_16x16x32_bf16 v[124:127], v[150:153], v[176:179], v[124:127]
	v_mfma_f32_16x16x32_bf16 v[120:123], v[168:171], v[176:179], v[120:123]
	v_mfma_f32_16x16x32_bf16 v[108:111], v[150:153], v[184:187], v[108:111]
	v_mfma_f32_16x16x32_bf16 v[104:107], v[168:171], v[184:187], v[104:107]
	v_mfma_f32_16x16x32_bf16 v[92:95], v[150:153], v[192:195], v[92:95]
	v_mfma_f32_16x16x32_bf16 v[88:91], v[168:171], v[192:195], v[88:91]
	v_mfma_f32_16x16x32_bf16 v[76:79], v[150:153], v[200:203], v[76:79]
	v_mfma_f32_16x16x32_bf16 v[72:75], v[168:171], v[200:203], v[72:75]
	s_setprio 0
	s_barrier
	s_add_i32 s30, 0, 0x1c000
	s_add_i32 s31, s67, s5
	v_add_u32_e32 v136, s30, v161
	v_lshl_add_u64 v[158:159], v[158:159], 0, s[18:19]
	s_mov_b32 m0, s31
	ds_read_b128 v[204:207], v136
	ds_read_b128 v[210:213], v136 offset:1024
	ds_read_b128 v[214:217], v136 offset:2048
	ds_read_b128 v[218:221], v136 offset:3072
	global_load_lds_dwordx4 v[158:159], off
	v_lshl_add_u64 v[158:159], v[222:223], 0, s[18:19]
	s_add_i32 m0, s31, 0x2000
	s_nop 0
	global_load_lds_dwordx4 v[158:159], off
	s_barrier
	s_waitcnt lgkmcnt(0)
	s_setprio 1
	s_waitcnt lgkmcnt(0)
	v_mfma_f32_16x16x32_bf16 v[116:119], v[204:207], v[172:175], v[116:119]
	v_mfma_f32_16x16x32_bf16 v[112:115], v[214:217], v[172:175], v[112:115]
	v_mfma_f32_16x16x32_bf16 v[100:103], v[204:207], v[180:183], v[100:103]
	v_mfma_f32_16x16x32_bf16 v[96:99], v[214:217], v[180:183], v[96:99]
	v_mfma_f32_16x16x32_bf16 v[84:87], v[204:207], v[188:191], v[84:87]
	v_mfma_f32_16x16x32_bf16 v[80:83], v[214:217], v[188:191], v[80:83]
	v_mfma_f32_16x16x32_bf16 v[68:71], v[204:207], v[196:199], v[68:71]
	v_mfma_f32_16x16x32_bf16 v[64:67], v[214:217], v[196:199], v[64:67]
	v_mfma_f32_16x16x32_bf16 v[116:119], v[210:213], v[176:179], v[116:119]
	v_mfma_f32_16x16x32_bf16 v[112:115], v[218:221], v[176:179], v[112:115]
	v_mfma_f32_16x16x32_bf16 v[100:103], v[210:213], v[184:187], v[100:103]
	v_mfma_f32_16x16x32_bf16 v[96:99], v[218:221], v[184:187], v[96:99]
	v_mfma_f32_16x16x32_bf16 v[84:87], v[210:213], v[192:195], v[84:87]
	v_mfma_f32_16x16x32_bf16 v[80:83], v[218:221], v[192:195], v[80:83]
	v_mfma_f32_16x16x32_bf16 v[68:71], v[210:213], v[200:203], v[68:71]
	v_mfma_f32_16x16x32_bf16 v[64:67], v[218:221], v[200:203], v[64:67]
	s_setprio 0
	s_mov_b32 m0, s37
	v_lshl_add_u64 v[158:159], v[224:225], 0, s[18:19]
	s_barrier
; DI u32 pack2(float a, float b) { f32v2 v = {a, b}; return __builtin_bit_cast(u32, __builtin_convertvector(v, bf16v2)); }
; #define PG8_STAGE(bufoff, gbase, voff) do { _Pragma("unroll") for (int _i = 0; _i < 2; ++_i) \
;     __builtin_amdgcn_global_load_lds((const unsigned*)((const char*)(gbase) + (voff)[_i]), (LAS unsigned*)(lds + (bufoff) + ldsw + _i * 8192), 16, 0, 0); } while (0)
; #define PG8_WAIT_V(n) asm volatile("s_waitcnt vmcnt(" #n ")" ::: "memory")
; #define PG8_WAIT_L(n) asm volatile("s_waitcnt lgkmcnt(" #n ")" ::: "memory")
; template <class Epi>
; DI void gemm_phase(LAS unsigned char* lds, const Gemm g, const StaticOrder& S, const Epi& E) {
;     ...
;       PG8_LDB(B1, 1, 1); PG8_STAGE(PG8_SB(1, 0), b3, voffB);
;       PG8_BAR; PG8_WAIT_L(0); PG8_MMA(0, 1, At, B1); PG8_BAR;
;       PG8_LDA(At, 1, 1); PG8_STAGE(PG8_SA(1, 0), a3, voffA);
;       PG8_BAR; PG8_WAIT_L(0); PG8_MMA(1, 0, At, B0); PG8_BAR; PG8_SCHED;
;       PG8_STAGE(PG8_SB(1, 1), b3 + hstep, voffB);
;       PG8_WAIT_V(6); PG8_BAR; PG8_MMA(1, 1, At, B1); PG8_BAR;
;   DI void operator()(const f32x4 (&acc)[2][2][4][2], const Unit& u, int wr, int wc, int fr, int fq) const {
;     const int row0 = u.pm * BM + wr * 64 + fr, colt = u.pn * BM, col0 = colt + wc * 32 + 8 * fq;
;     const bool kv = (mode == 1) && colt >= 2048 && colt < 6144;
;     const int sec = colt >= 4096 ? 1 : 0;
; #pragma unroll
;     for (int ai = 0; ai < 2; ++ai)
; #pragma unroll
;       for (int m = 0; m < 4; ++m) {
;         const int row = row0 + ai * HALF + m * 16;
;         u16* rowp = O + (size_t)row * ldc + col0;
;         const float rr = rs ? rsqrtf(rs[row] * (1.f / 2048.f) + 1e-6f) : 1.f;
; #pragma unroll
;         for (int bj = 0; bj < 2; ++bj) {
;           const f32x4 v0 = acc[ai][bj][m][0] * rr, v1 = acc[ai][bj][m][1] * rr;
;           u32x4 w = {pack2(v0[0], v0[1]), pack2(v0[2], v0[3]), pack2(v1[0], v1[1]), pack2(v1[2], v1[3])};
;           *reinterpret_cast<u32x4*>(rowp + bj * HALF) = w;
;           if (kv) {
;             const int c2 = col0 + bj * HALF - 2048 - sec * 2048;
;             float* dst = row < PROWS ? out + (sec ? OFF_VP : OFF_KP) + (size_t)row * DM + c2 : out + (sec ? OFF_VS : OFF_KS) + (size_t)(row - PROWS) * DM + c2;
;             __builtin_nontemporal_store(v0, reinterpret_cast<f32x4*>(dst)); __builtin_nontemporal_store(v1, reinterpret_cast<f32x4*>(dst + 4));
	ds_read_b128 v[172:175], v164 offset:49152
	ds_read_b128 v[176:179], v164 offset:50176
	ds_read_b128 v[180:183], v164 offset:51200
	ds_read_b128 v[184:187], v164 offset:52224
	ds_read_b128 v[188:191], v164 offset:53248
	ds_read_b128 v[192:195], v164 offset:54272
	ds_read_b128 v[196:199], v164 offset:55296
	ds_read_b128 v[200:203], v164 offset:56320
	global_load_lds_dwordx4 v[158:159], off
	v_lshl_add_u64 v[158:159], v[226:227], 0, s[18:19]
	s_mov_b32 m0, s38
	s_nop 0
	global_load_lds_dwordx4 v[158:159], off
	s_barrier
	s_waitcnt lgkmcnt(0)
	s_setprio 1
	s_waitcnt lgkmcnt(0)
	v_mfma_f32_16x16x32_bf16 v[60:63], v[146:149], v[172:175], v[60:63]
	v_mfma_f32_16x16x32_bf16 v[56:59], v[154:157], v[172:175], v[56:59]
	v_mfma_f32_16x16x32_bf16 v[44:47], v[146:149], v[180:183], v[44:47]
	v_mfma_f32_16x16x32_bf16 v[40:43], v[154:157], v[180:183], v[40:43]
	v_mfma_f32_16x16x32_bf16 v[28:31], v[146:149], v[188:191], v[28:31]
	v_mfma_f32_16x16x32_bf16 v[24:27], v[154:157], v[188:191], v[24:27]
	v_mfma_f32_16x16x32_bf16 v[12:15], v[146:149], v[196:199], v[12:15]
	v_mfma_f32_16x16x32_bf16 v[8:11], v[154:157], v[196:199], v[8:11]
	v_mfma_f32_16x16x32_bf16 v[60:63], v[150:153], v[176:179], v[60:63]
	v_mfma_f32_16x16x32_bf16 v[56:59], v[168:171], v[176:179], v[56:59]
	v_mfma_f32_16x16x32_bf16 v[44:47], v[150:153], v[184:187], v[44:47]
	v_mfma_f32_16x16x32_bf16 v[40:43], v[168:171], v[184:187], v[40:43]
	v_mfma_f32_16x16x32_bf16 v[28:31], v[150:153], v[192:195], v[28:31]
	v_mfma_f32_16x16x32_bf16 v[24:27], v[168:171], v[192:195], v[24:27]
	v_mfma_f32_16x16x32_bf16 v[12:15], v[150:153], v[200:203], v[12:15]
	v_mfma_f32_16x16x32_bf16 v[8:11], v[168:171], v[200:203], v[8:11]
	s_setprio 0
	s_barrier
	s_add_u32 s28, s28, 0x80080
	s_addc_u32 s29, s29, 0
	s_add_i32 s30, s30, s5
	v_lshl_add_u64 v[146:147], s[28:29], 0, v[130:131]
	s_mov_b32 m0, s30
	s_nop 0
	global_load_lds_dwordx4 v[146:147], off
	v_lshl_add_u64 v[146:147], s[28:29], 0, v[134:135]
	s_add_i32 m0, s30, 0x2000
	s_nop 0
	global_load_lds_dwordx4 v[146:147], off
	s_waitcnt vmcnt(6)
	s_barrier
	s_setprio 1
	v_mfma_f32_16x16x32_bf16 v[52:55], v[204:207], v[172:175], v[52:55]
	v_mfma_f32_16x16x32_bf16 v[48:51], v[214:217], v[172:175], v[48:51]
	v_mfma_f32_16x16x32_bf16 v[36:39], v[204:207], v[180:183], v[36:39]
	v_mfma_f32_16x16x32_bf16 v[32:35], v[214:217], v[180:183], v[32:35]
	v_mfma_f32_16x16x32_bf16 v[20:23], v[204:207], v[188:191], v[20:23]
	v_mfma_f32_16x16x32_bf16 v[16:19], v[214:217], v[188:191], v[16:19]
	v_mfma_f32_16x16x32_bf16 v[4:7], v[204:207], v[196:199], v[4:7]
	v_mfma_f32_16x16x32_bf16 v[0:3], v[214:217], v[196:199], v[0:3]
	v_mfma_f32_16x16x32_bf16 v[52:55], v[210:213], v[176:179], v[52:55]
	v_mfma_f32_16x16x32_bf16 v[48:51], v[218:221], v[176:179], v[48:51]
	v_mfma_f32_16x16x32_bf16 v[36:39], v[210:213], v[184:187], v[36:39]
	v_mfma_f32_16x16x32_bf16 v[32:35], v[218:221], v[184:187], v[32:35]
	v_mfma_f32_16x16x32_bf16 v[20:23], v[210:213], v[192:195], v[20:23]
	v_mfma_f32_16x16x32_bf16 v[16:19], v[218:221], v[192:195], v[16:19]
	v_mfma_f32_16x16x32_bf16 v[4:7], v[210:213], v[200:203], v[4:7]
	v_mfma_f32_16x16x32_bf16 v[0:3], v[218:221], v[200:203], v[0:3]
	s_setprio 0
	s_add_i32 s66, s66, 2
	s_add_u32 s64, s64, 0x100
	s_addc_u32 s65, s65, 0
	s_add_u32 s14, s14, 0x100
	s_addc_u32 s15, s15, 0
	s_cmp_gt_u32 s66, 29
	s_barrier
	s_cbranch_scc0 .LBB0_867
	v_lshl_add_u32 v148, s12, 8, v160
	v_ashrrev_i32_e32 v149, 31, v148
	v_lshl_add_u64 v[152:153], v[148:149], 2, s[16:17]
	global_load_dword v158, v[152:153], off
	global_load_dword v174, v[152:153], off offset:64
	global_load_dword v175, v[152:153], off offset:128
	global_load_dword v176, v[152:153], off offset:192
	global_load_dword v177, v[152:153], off offset:512
	global_load_dword v178, v[152:153], off offset:576
	global_load_dword v179, v[152:153], off offset:640
	global_load_dword v180, v[152:153], off offset:704
	v_add_u32_e32 v136, 0xffffc000, v148
	v_lshlrev_b64 v[146:147], 14, v[148:149]
	v_lshlrev_b64 v[154:155], 13, v[136:137]
	v_lshl_add_u64 v[156:157], s[56:57], 0, v[146:147]
	s_add_i32 s11, s10, -8
	s_cmp_lt_u32 s11, 16
	s_cselect_b64 s[14:15], -1, 0
	s_cmp_gt_i32 s10, 15
	v_lshlrev_b64 v[172:173], 13, v[148:149]
	v_lshl_or_b32 v150, s10, 8, v162
	s_cselect_b32 s10, s48, 0xfffff800
	v_ashrrev_i32_e32 v151, 31, v150
	v_cmp_gt_i32_e64 s[12:13], s36, v148
	s_cselect_b32 s21, s49, 0x6f80000
	s_cselect_b32 s23, s50, 0x2f80000
	s_cmp_gt_u32 s11, 15
	v_cndmask_b32_e64 v155, v155, v173, s[12:13]
	v_lshl_add_u64 v[156:157], v[150:151], 1, v[156:157]
	v_cndmask_b32_e64 v154, v154, v172, s[12:13]
	s_waitcnt vmcnt(0)
	v_fmamk_f32 v136, v158, 0x3a000000, v166
	v_mul_f32_e32 v146, 0x4b800000, v136
	v_cmp_gt_f32_e32 vcc, s51, v136
	s_nop 1
	v_cndmask_b32_e32 v136, v136, v146, vcc
	v_rsq_f32_e32 v136, v136
	v_add_u32_e32 v146, s10, v150
	v_ashrrev_i32_e32 v147, 31, v146
	v_mul_f32_e32 v149, 0x45800000, v136
	v_cndmask_b32_e32 v158, v136, v149, vcc
	v_pk_mul_f32 v[126:127], v[126:127], v[158:159] op_sel_hi:[1,0]
	v_pk_mul_f32 v[124:125], v[124:125], v[158:159] op_sel_hi:[1,0]
	v_pk_mul_f32 v[122:123], v[122:123], v[158:159] op_sel_hi:[1,0]
	v_pk_mul_f32 v[120:121], v[120:121], v[158:159] op_sel_hi:[1,0]
	v_cvt_pk_bf16_f32 v168, v124, v125
	v_cvt_pk_bf16_f32 v169, v126, v127
	v_cvt_pk_bf16_f32 v170, v120, v121
	v_cvt_pk_bf16_f32 v171, v122, v123
	global_store_dwordx4 v[156:157], v[168:171], off
	s_cbranch_scc1 .LBB0_870
	v_mov_b32_e32 v136, s21
	v_mov_b32_e32 v149, s23
	v_cndmask_b32_e64 v136, v136, v149, s[12:13]
	v_lshlrev_b32_e32 v136, 2, v136
	v_lshl_add_u64 v[168:169], s[44:45], 0, v[136:137]
	v_lshl_add_u64 v[168:169], v[168:169], 0, v[154:155]
	v_lshl_add_u64 v[168:169], v[146:147], 2, v[168:169]
	global_store_dwordx4 v[168:169], v[124:127], off nt
	global_store_dwordx4 v[168:169], v[120:123], off offset:16 nt

; DI u32 pack2(float a, float b) { f32v2 v = {a, b}; return __builtin_bit_cast(u32, __builtin_convertvector(v, bf16v2)); }
;   DI void operator()(const f32x4 (&acc)[2][2][4][2], const Unit& u, int wr, int wc, int fr, int fq) const {
;     ...
;         const int row = row0 + ai * HALF + m * 16;
;         u16* rowp = O + (size_t)row * ldc + col0;
;         const float rr = rs ? rsqrtf(rs[row] * (1.f / 2048.f) + 1e-6f) : 1.f;
; #pragma unroll
;         for (int bj = 0; bj < 2; ++bj) {
;           const f32x4 v0 = acc[ai][bj][m][0] * rr, v1 = acc[ai][bj][m][1] * rr;
;           u32x4 w = {pack2(v0[0], v0[1]), pack2(v0[2], v0[3]), pack2(v1[0], v1[1]), pack2(v1[2], v1[3])};
;           *reinterpret_cast<u32x4*>(rowp + bj * HALF) = w;
;           if (kv) {
;             const int c2 = col0 + bj * HALF - 2048 - sec * 2048;
;             float* dst = row < PROWS ? out + (sec ? OFF_VP : OFF_KP) + (size_t)row * DM + c2 : out + (sec ? OFF_VS : OFF_KS) + (size_t)(row - PROWS) * DM + c2;
;             __builtin_nontemporal_store(v0, reinterpret_cast<f32x4*>(dst)); __builtin_nontemporal_store(v1, reinterpret_cast<f32x4*>(dst + 4));
.LBB0_872:
	s_nop 1
	v_or_b32_e32 v112, 16, v148
	v_ashrrev_i32_e32 v113, 31, v112
	v_lshl_add_u64 v[114:115], v[112:113], 2, s[16:17]
	s_nop 1
	v_mov_b32_e32 v116, v174
	v_lshlrev_b64 v[114:115], 14, v[112:113]
	v_lshlrev_b64 v[124:125], 13, v[112:113]
	v_cmp_gt_i32_e64 s[12:13], s36, v112
	v_add_u32_e32 v136, 0xffffc010, v148
	v_lshlrev_b64 v[122:123], 13, v[136:137]
	v_lshl_add_u64 v[114:115], s[56:57], 0, v[114:115]
	s_and_b64 vcc, exec, s[10:11]
	v_lshl_add_u64 v[114:115], v[150:151], 1, v[114:115]
	v_fmamk_f32 v113, v116, 0x3a000000, v166
	v_mul_f32_e32 v116, 0x4b800000, v113
	v_cmp_gt_f32_e64 s[14:15], s51, v113
	s_nop 1
	v_cndmask_b32_e64 v113, v113, v116, s[14:15]
	v_rsq_f32_e32 v116, v113
	v_cndmask_b32_e64 v113, v123, v125, s[12:13]
	v_mul_f32_e32 v112, 0x45800000, v116
	v_cndmask_b32_e64 v116, v116, v112, s[14:15]
	v_pk_mul_f32 v[110:111], v[110:111], v[116:117] op_sel_hi:[1,0]
	v_pk_mul_f32 v[108:109], v[108:109], v[116:117] op_sel_hi:[1,0]
	v_pk_mul_f32 v[106:107], v[106:107], v[116:117] op_sel_hi:[1,0]
	v_pk_mul_f32 v[104:105], v[104:105], v[116:117] op_sel_hi:[1,0]
	v_cvt_pk_bf16_f32 v118, v108, v109
	v_cvt_pk_bf16_f32 v119, v110, v111
	v_cvt_pk_bf16_f32 v120, v104, v105
	v_cvt_pk_bf16_f32 v121, v106, v107
	v_cndmask_b32_e64 v112, v122, v124, s[12:13]
	global_store_dwordx4 v[114:115], v[118:121], off
	s_cbranch_vccnz .LBB0_874
	v_mov_b32_e32 v117, s21
	v_mov_b32_e32 v118, s23
	v_cndmask_b32_e64 v117, v117, v118, s[12:13]
	v_lshlrev_b32_e32 v136, 2, v117
	v_lshl_add_u64 v[118:119], s[44:45], 0, v[136:137]
	v_lshl_add_u64 v[118:119], v[118:119], 0, v[112:113]
	v_lshl_add_u64 v[118:119], v[146:147], 2, v[118:119]
	global_store_dwordx4 v[118:119], v[108:111], off nt
	global_store_dwordx4 v[118:119], v[104:107], off offset:16 nt

; DI u32 pack2(float a, float b) { f32v2 v = {a, b}; return __builtin_bit_cast(u32, __builtin_convertvector(v, bf16v2)); }
;   DI void operator()(const f32x4 (&acc)[2][2][4][2], const Unit& u, int wr, int wc, int fr, int fq) const {
;     ...
;         const int row = row0 + ai * HALF + m * 16;
;         u16* rowp = O + (size_t)row * ldc + col0;
;         const float rr = rs ? rsqrtf(rs[row] * (1.f / 2048.f) + 1e-6f) : 1.f;
; #pragma unroll
;         for (int bj = 0; bj < 2; ++bj) {
;           const f32x4 v0 = acc[ai][bj][m][0] * rr, v1 = acc[ai][bj][m][1] * rr;
;           u32x4 w = {pack2(v0[0], v0[1]), pack2(v0[2], v0[3]), pack2(v1[0], v1[1]), pack2(v1[2], v1[3])};
;           *reinterpret_cast<u32x4*>(rowp + bj * HALF) = w;
;           if (kv) {
;             const int c2 = col0 + bj * HALF - 2048 - sec * 2048;
;             float* dst = row < PROWS ? out + (sec ? OFF_VP : OFF_KP) + (size_t)row * DM + c2 : out + (sec ? OFF_VS : OFF_KS) + (size_t)(row - PROWS) * DM + c2;
;             __builtin_nontemporal_store(v0, reinterpret_cast<f32x4*>(dst)); __builtin_nontemporal_store(v1, reinterpret_cast<f32x4*>(dst + 4));
.LBB0_876:
	s_nop 1
	v_or_b32_e32 v96, 32, v148
	v_ashrrev_i32_e32 v97, 31, v96
	v_lshl_add_u64 v[98:99], v[96:97], 2, s[16:17]
	s_nop 1
	v_mov_b32_e32 v100, v175
	v_lshlrev_b64 v[98:99], 14, v[96:97]
	v_lshlrev_b64 v[108:109], 13, v[96:97]
	v_cmp_gt_i32_e64 s[12:13], s36, v96
	v_add_u32_e32 v136, 0xffffc020, v148
	v_lshlrev_b64 v[106:107], 13, v[136:137]
	v_lshl_add_u64 v[98:99], s[56:57], 0, v[98:99]
	s_and_b64 vcc, exec, s[10:11]
	v_lshl_add_u64 v[98:99], v[150:151], 1, v[98:99]
	v_fmamk_f32 v97, v100, 0x3a000000, v166
	v_mul_f32_e32 v100, 0x4b800000, v97
	v_cmp_gt_f32_e64 s[14:15], s51, v97
	s_nop 1
	v_cndmask_b32_e64 v97, v97, v100, s[14:15]
	v_rsq_f32_e32 v100, v97
	v_cndmask_b32_e64 v97, v107, v109, s[12:13]
	v_mul_f32_e32 v96, 0x45800000, v100
	v_cndmask_b32_e64 v100, v100, v96, s[14:15]
	v_pk_mul_f32 v[94:95], v[94:95], v[100:101] op_sel_hi:[1,0]
	v_pk_mul_f32 v[92:93], v[92:93], v[100:101] op_sel_hi:[1,0]
	v_pk_mul_f32 v[90:91], v[90:91], v[100:101] op_sel_hi:[1,0]
	v_pk_mul_f32 v[88:89], v[88:89], v[100:101] op_sel_hi:[1,0]
	v_cvt_pk_bf16_f32 v102, v92, v93
	v_cvt_pk_bf16_f32 v103, v94, v95
	v_cvt_pk_bf16_f32 v104, v88, v89
	v_cvt_pk_bf16_f32 v105, v90, v91
	v_cndmask_b32_e64 v96, v106, v108, s[12:13]
	global_store_dwordx4 v[98:99], v[102:105], off
	s_cbranch_vccnz .LBB0_878
	v_mov_b32_e32 v101, s21
	v_mov_b32_e32 v102, s23
	v_cndmask_b32_e64 v101, v101, v102, s[12:13]
	v_lshlrev_b32_e32 v136, 2, v101
	v_lshl_add_u64 v[102:103], s[44:45], 0, v[136:137]
	v_lshl_add_u64 v[102:103], v[102:103], 0, v[96:97]
	v_lshl_add_u64 v[102:103], v[146:147], 2, v[102:103]
	global_store_dwordx4 v[102:103], v[92:95], off nt
	global_store_dwordx4 v[102:103], v[88:91], off offset:16 nt

; DI u32 pack2(float a, float b) { f32v2 v = {a, b}; return __builtin_bit_cast(u32, __builtin_convertvector(v, bf16v2)); }
;   DI void operator()(const f32x4 (&acc)[2][2][4][2], const Unit& u, int wr, int wc, int fr, int fq) const {
;     ...
;         const int row = row0 + ai * HALF + m * 16;
;         u16* rowp = O + (size_t)row * ldc + col0;
;         const float rr = rs ? rsqrtf(rs[row] * (1.f / 2048.f) + 1e-6f) : 1.f;
; #pragma unroll
;         for (int bj = 0; bj < 2; ++bj) {
;           const f32x4 v0 = acc[ai][bj][m][0] * rr, v1 = acc[ai][bj][m][1] * rr;
;           u32x4 w = {pack2(v0[0], v0[1]), pack2(v0[2], v0[3]), pack2(v1[0], v1[1]), pack2(v1[2], v1[3])};
;           *reinterpret_cast<u32x4*>(rowp + bj * HALF) = w;
;           if (kv) {
;             const int c2 = col0 + bj * HALF - 2048 - sec * 2048;
;             float* dst = row < PROWS ? out + (sec ? OFF_VP : OFF_KP) + (size_t)row * DM + c2 : out + (sec ? OFF_VS : OFF_KS) + (size_t)(row - PROWS) * DM + c2;
;             __builtin_nontemporal_store(v0, reinterpret_cast<f32x4*>(dst)); __builtin_nontemporal_store(v1, reinterpret_cast<f32x4*>(dst + 4));
.LBB0_880:
	s_nop 1
	v_or_b32_e32 v80, 48, v148
	v_ashrrev_i32_e32 v81, 31, v80
	v_lshl_add_u64 v[82:83], v[80:81], 2, s[16:17]
	s_nop 1
	v_mov_b32_e32 v84, v176
	v_lshlrev_b64 v[82:83], 14, v[80:81]
	v_lshlrev_b64 v[92:93], 13, v[80:81]
	v_cmp_gt_i32_e64 s[12:13], s36, v80
	v_add_u32_e32 v136, 0xffffc030, v148
	v_lshlrev_b64 v[90:91], 13, v[136:137]
	v_lshl_add_u64 v[82:83], s[56:57], 0, v[82:83]
	s_and_b64 vcc, exec, s[10:11]
	v_lshl_add_u64 v[82:83], v[150:151], 1, v[82:83]
	v_fmamk_f32 v81, v84, 0x3a000000, v166
	v_mul_f32_e32 v84, 0x4b800000, v81
	v_cmp_gt_f32_e64 s[14:15], s51, v81
	s_nop 1
	v_cndmask_b32_e64 v81, v81, v84, s[14:15]
	v_rsq_f32_e32 v84, v81
	v_cndmask_b32_e64 v81, v91, v93, s[12:13]
	v_mul_f32_e32 v80, 0x45800000, v84
	v_cndmask_b32_e64 v84, v84, v80, s[14:15]
	v_pk_mul_f32 v[78:79], v[78:79], v[84:85] op_sel_hi:[1,0]
	v_pk_mul_f32 v[76:77], v[76:77], v[84:85] op_sel_hi:[1,0]
	v_pk_mul_f32 v[74:75], v[74:75], v[84:85] op_sel_hi:[1,0]
	v_pk_mul_f32 v[72:73], v[72:73], v[84:85] op_sel_hi:[1,0]
	v_cvt_pk_bf16_f32 v86, v76, v77
	v_cvt_pk_bf16_f32 v87, v78, v79
	v_cvt_pk_bf16_f32 v88, v72, v73
	v_cvt_pk_bf16_f32 v89, v74, v75
	v_cndmask_b32_e64 v80, v90, v92, s[12:13]
	global_store_dwordx4 v[82:83], v[86:89], off
	s_cbranch_vccnz .LBB0_882
	v_mov_b32_e32 v85, s21
	v_mov_b32_e32 v86, s23
	v_cndmask_b32_e64 v85, v85, v86, s[12:13]
	v_lshlrev_b32_e32 v136, 2, v85
	v_lshl_add_u64 v[86:87], s[44:45], 0, v[136:137]
	v_lshl_add_u64 v[86:87], v[86:87], 0, v[80:81]
	v_lshl_add_u64 v[86:87], v[146:147], 2, v[86:87]
	global_store_dwordx4 v[86:87], v[76:79], off nt
	global_store_dwordx4 v[86:87], v[72:75], off offset:16 nt

; DI u32 pack2(float a, float b) { f32v2 v = {a, b}; return __builtin_bit_cast(u32, __builtin_convertvector(v, bf16v2)); }
;   DI void operator()(const f32x4 (&acc)[2][2][4][2], const Unit& u, int wr, int wc, int fr, int fq) const {
;     ...
;         const int row = row0 + ai * HALF + m * 16;
;         u16* rowp = O + (size_t)row * ldc + col0;
;         const float rr = rs ? rsqrtf(rs[row] * (1.f / 2048.f) + 1e-6f) : 1.f;
; #pragma unroll
;         for (int bj = 0; bj < 2; ++bj) {
;           const f32x4 v0 = acc[ai][bj][m][0] * rr, v1 = acc[ai][bj][m][1] * rr;
;           u32x4 w = {pack2(v0[0], v0[1]), pack2(v0[2], v0[3]), pack2(v1[0], v1[1]), pack2(v1[2], v1[3])};
;           *reinterpret_cast<u32x4*>(rowp + bj * HALF) = w;
;           if (kv) {
;             const int c2 = col0 + bj * HALF - 2048 - sec * 2048;
;             float* dst = row < PROWS ? out + (sec ? OFF_VP : OFF_KP) + (size_t)row * DM + c2 : out + (sec ? OFF_VS : OFF_KS) + (size_t)(row - PROWS) * DM + c2;
;             __builtin_nontemporal_store(v0, reinterpret_cast<f32x4*>(dst)); __builtin_nontemporal_store(v1, reinterpret_cast<f32x4*>(dst + 4));
.LBB0_884:
	s_nop 1
	v_mov_b32_e32 v68, v177
	s_nop 0
	v_add_u32_e32 v64, 0x80, v148
	v_ashrrev_i32_e32 v65, 31, v64
	v_add_u32_e32 v136, 0xffffc080, v148
	v_lshlrev_b64 v[66:67], 14, v[64:65]
	v_lshlrev_b64 v[74:75], 13, v[136:137]
	v_lshlrev_b64 v[64:65], 13, v[64:65]
	v_lshl_add_u64 v[66:67], s[56:57], 0, v[66:67]
	v_cmp_gt_i32_e64 s[12:13], s54, v148
	s_and_b64 vcc, exec, s[10:11]
	v_lshl_add_u64 v[66:67], v[150:151], 1, v[66:67]
	v_cndmask_b32_e64 v65, v75, v65, s[12:13]
	v_cndmask_b32_e64 v64, v74, v64, s[12:13]
	v_fmamk_f32 v68, v68, 0x3a000000, v166
	v_mul_f32_e32 v69, 0x4b800000, v68
	v_cmp_gt_f32_e64 s[14:15], s51, v68
	s_nop 1
	v_cndmask_b32_e64 v68, v68, v69, s[14:15]
	v_rsq_f32_e32 v68, v68
	s_nop 0
	v_mul_f32_e32 v69, 0x45800000, v68
	v_cndmask_b32_e64 v68, v68, v69, s[14:15]
	v_pk_mul_f32 v[62:63], v[62:63], v[68:69] op_sel_hi:[1,0]
	v_pk_mul_f32 v[60:61], v[60:61], v[68:69] op_sel_hi:[1,0]
	v_pk_mul_f32 v[58:59], v[58:59], v[68:69] op_sel_hi:[1,0]
	v_pk_mul_f32 v[56:57], v[56:57], v[68:69] op_sel_hi:[1,0]
	v_cvt_pk_bf16_f32 v70, v60, v61
	v_cvt_pk_bf16_f32 v71, v62, v63
	v_cvt_pk_bf16_f32 v72, v56, v57
	v_cvt_pk_bf16_f32 v73, v58, v59
	global_store_dwordx4 v[66:67], v[70:73], off
	s_cbranch_vccnz .LBB0_886
	v_mov_b32_e32 v69, s21
	v_mov_b32_e32 v70, s23
	v_cndmask_b32_e64 v69, v69, v70, s[12:13]
	v_lshlrev_b32_e32 v136, 2, v69
	v_lshl_add_u64 v[70:71], s[44:45], 0, v[136:137]
	v_lshl_add_u64 v[70:71], v[70:71], 0, v[64:65]
	v_lshl_add_u64 v[70:71], v[146:147], 2, v[70:71]
	global_store_dwordx4 v[70:71], v[60:63], off nt
	global_store_dwordx4 v[70:71], v[56:59], off offset:16 nt

; DI u32 pack2(float a, float b) { f32v2 v = {a, b}; return __builtin_bit_cast(u32, __builtin_convertvector(v, bf16v2)); }
;   DI void operator()(const f32x4 (&acc)[2][2][4][2], const Unit& u, int wr, int wc, int fr, int fq) const {
;     ...
;         const int row = row0 + ai * HALF + m * 16;
;         u16* rowp = O + (size_t)row * ldc + col0;
;         const float rr = rs ? rsqrtf(rs[row] * (1.f / 2048.f) + 1e-6f) : 1.f;
; #pragma unroll
;         for (int bj = 0; bj < 2; ++bj) {
;           const f32x4 v0 = acc[ai][bj][m][0] * rr, v1 = acc[ai][bj][m][1] * rr;
;           u32x4 w = {pack2(v0[0], v0[1]), pack2(v0[2], v0[3]), pack2(v1[0], v1[1]), pack2(v1[2], v1[3])};
;           *reinterpret_cast<u32x4*>(rowp + bj * HALF) = w;
;           if (kv) {
;             const int c2 = col0 + bj * HALF - 2048 - sec * 2048;
;             float* dst = row < PROWS ? out + (sec ? OFF_VP : OFF_KP) + (size_t)row * DM + c2 : out + (sec ? OFF_VS : OFF_KS) + (size_t)(row - PROWS) * DM + c2;
;             __builtin_nontemporal_store(v0, reinterpret_cast<f32x4*>(dst)); __builtin_nontemporal_store(v1, reinterpret_cast<f32x4*>(dst + 4));
.LBB0_888:
	s_nop 1
	v_mov_b32_e32 v52, v178
	s_nop 0
	v_add_u32_e32 v48, 0x90, v148
	v_ashrrev_i32_e32 v49, 31, v48
	v_add_u32_e32 v136, 0xffffc090, v148
	v_lshlrev_b64 v[50:51], 14, v[48:49]
	v_lshlrev_b64 v[58:59], 13, v[136:137]
	v_lshlrev_b64 v[48:49], 13, v[48:49]
	v_lshl_add_u64 v[50:51], s[56:57], 0, v[50:51]
	v_cmp_gt_i32_e64 s[12:13], s55, v148
	s_and_b64 vcc, exec, s[10:11]
	v_lshl_add_u64 v[50:51], v[150:151], 1, v[50:51]
	v_cndmask_b32_e64 v49, v59, v49, s[12:13]
	v_cndmask_b32_e64 v48, v58, v48, s[12:13]
	v_fmamk_f32 v52, v52, 0x3a000000, v166
	v_mul_f32_e32 v53, 0x4b800000, v52
	v_cmp_gt_f32_e64 s[14:15], s51, v52
	s_nop 1
	v_cndmask_b32_e64 v52, v52, v53, s[14:15]
	v_rsq_f32_e32 v52, v52
	s_nop 0
	v_mul_f32_e32 v53, 0x45800000, v52
	v_cndmask_b32_e64 v52, v52, v53, s[14:15]
	v_pk_mul_f32 v[46:47], v[46:47], v[52:53] op_sel_hi:[1,0]
	v_pk_mul_f32 v[44:45], v[44:45], v[52:53] op_sel_hi:[1,0]
	v_pk_mul_f32 v[42:43], v[42:43], v[52:53] op_sel_hi:[1,0]
	v_pk_mul_f32 v[40:41], v[40:41], v[52:53] op_sel_hi:[1,0]
	v_cvt_pk_bf16_f32 v54, v44, v45
	v_cvt_pk_bf16_f32 v55, v46, v47
	v_cvt_pk_bf16_f32 v56, v40, v41
	v_cvt_pk_bf16_f32 v57, v42, v43
	global_store_dwordx4 v[50:51], v[54:57], off
	s_cbranch_vccnz .LBB0_890
	v_mov_b32_e32 v53, s21
	v_mov_b32_e32 v54, s23
	v_cndmask_b32_e64 v53, v53, v54, s[12:13]
	v_lshlrev_b32_e32 v136, 2, v53
	v_lshl_add_u64 v[54:55], s[44:45], 0, v[136:137]
	v_lshl_add_u64 v[54:55], v[54:55], 0, v[48:49]
	v_lshl_add_u64 v[54:55], v[146:147], 2, v[54:55]
	global_store_dwordx4 v[54:55], v[44:47], off nt
	global_store_dwordx4 v[54:55], v[40:43], off offset:16 nt

; DI u32 pack2(float a, float b) { f32v2 v = {a, b}; return __builtin_bit_cast(u32, __builtin_convertvector(v, bf16v2)); }
;   DI void operator()(const f32x4 (&acc)[2][2][4][2], const Unit& u, int wr, int wc, int fr, int fq) const {
;     ...
;         const int row = row0 + ai * HALF + m * 16;
;         u16* rowp = O + (size_t)row * ldc + col0;
;         const float rr = rs ? rsqrtf(rs[row] * (1.f / 2048.f) + 1e-6f) : 1.f;
; #pragma unroll
;         for (int bj = 0; bj < 2; ++bj) {
;           const f32x4 v0 = acc[ai][bj][m][0] * rr, v1 = acc[ai][bj][m][1] * rr;
;           u32x4 w = {pack2(v0[0], v0[1]), pack2(v0[2], v0[3]), pack2(v1[0], v1[1]), pack2(v1[2], v1[3])};
;           *reinterpret_cast<u32x4*>(rowp + bj * HALF) = w;
;           if (kv) {
;             const int c2 = col0 + bj * HALF - 2048 - sec * 2048;
;             float* dst = row < PROWS ? out + (sec ? OFF_VP : OFF_KP) + (size_t)row * DM + c2 : out + (sec ? OFF_VS : OFF_KS) + (size_t)(row - PROWS) * DM + c2;
;             __builtin_nontemporal_store(v0, reinterpret_cast<f32x4*>(dst)); __builtin_nontemporal_store(v1, reinterpret_cast<f32x4*>(dst + 4));
.LBB0_892:
	s_nop 1
	v_mov_b32_e32 v36, v179
	s_nop 0
	v_add_u32_e32 v32, 0xa0, v148
	v_ashrrev_i32_e32 v33, 31, v32
	v_add_u32_e32 v136, 0xffffc0a0, v148
	v_lshlrev_b64 v[34:35], 14, v[32:33]
	v_lshlrev_b64 v[42:43], 13, v[136:137]
	v_lshlrev_b64 v[32:33], 13, v[32:33]
	v_lshl_add_u64 v[34:35], s[56:57], 0, v[34:35]
	v_cmp_gt_i32_e64 s[12:13], s58, v148
	s_and_b64 vcc, exec, s[10:11]
	v_lshl_add_u64 v[34:35], v[150:151], 1, v[34:35]
	v_cndmask_b32_e64 v33, v43, v33, s[12:13]
	v_cndmask_b32_e64 v32, v42, v32, s[12:13]
	v_fmamk_f32 v36, v36, 0x3a000000, v166
	v_mul_f32_e32 v37, 0x4b800000, v36
	v_cmp_gt_f32_e64 s[14:15], s51, v36
	s_nop 1
	v_cndmask_b32_e64 v36, v36, v37, s[14:15]
	v_rsq_f32_e32 v36, v36
	s_nop 0
	v_mul_f32_e32 v37, 0x45800000, v36
	v_cndmask_b32_e64 v36, v36, v37, s[14:15]
	v_pk_mul_f32 v[30:31], v[30:31], v[36:37] op_sel_hi:[1,0]
	v_pk_mul_f32 v[28:29], v[28:29], v[36:37] op_sel_hi:[1,0]
	v_pk_mul_f32 v[26:27], v[26:27], v[36:37] op_sel_hi:[1,0]
	v_pk_mul_f32 v[24:25], v[24:25], v[36:37] op_sel_hi:[1,0]
	v_cvt_pk_bf16_f32 v38, v28, v29
	v_cvt_pk_bf16_f32 v39, v30, v31
	v_cvt_pk_bf16_f32 v40, v24, v25
	v_cvt_pk_bf16_f32 v41, v26, v27
	global_store_dwordx4 v[34:35], v[38:41], off
	s_cbranch_vccnz .LBB0_894
	v_mov_b32_e32 v37, s21
	v_mov_b32_e32 v38, s23
	v_cndmask_b32_e64 v37, v37, v38, s[12:13]
	v_lshlrev_b32_e32 v136, 2, v37
	v_lshl_add_u64 v[38:39], s[44:45], 0, v[136:137]
	v_lshl_add_u64 v[38:39], v[38:39], 0, v[32:33]
	v_lshl_add_u64 v[38:39], v[146:147], 2, v[38:39]
	global_store_dwordx4 v[38:39], v[28:31], off nt
	global_store_dwordx4 v[38:39], v[24:27], off offset:16 nt

; DI u32 pack2(float a, float b) { f32v2 v = {a, b}; return __builtin_bit_cast(u32, __builtin_convertvector(v, bf16v2)); }
;   DI void operator()(const f32x4 (&acc)[2][2][4][2], const Unit& u, int wr, int wc, int fr, int fq) const {
;     ...
;         const int row = row0 + ai * HALF + m * 16;
;         u16* rowp = O + (size_t)row * ldc + col0;
;         const float rr = rs ? rsqrtf(rs[row] * (1.f / 2048.f) + 1e-6f) : 1.f;
; #pragma unroll
;         for (int bj = 0; bj < 2; ++bj) {
;           const f32x4 v0 = acc[ai][bj][m][0] * rr, v1 = acc[ai][bj][m][1] * rr;
;           u32x4 w = {pack2(v0[0], v0[1]), pack2(v0[2], v0[3]), pack2(v1[0], v1[1]), pack2(v1[2], v1[3])};
;           *reinterpret_cast<u32x4*>(rowp + bj * HALF) = w;
;           if (kv) {
;             const int c2 = col0 + bj * HALF - 2048 - sec * 2048;
;             float* dst = row < PROWS ? out + (sec ? OFF_VP : OFF_KP) + (size_t)row * DM + c2 : out + (sec ? OFF_VS : OFF_KS) + (size_t)(row - PROWS) * DM + c2;
;             __builtin_nontemporal_store(v0, reinterpret_cast<f32x4*>(dst)); __builtin_nontemporal_store(v1, reinterpret_cast<f32x4*>(dst + 4));
.LBB0_896:
	s_nop 1
	v_mov_b32_e32 v20, v180
	s_nop 0
	v_add_u32_e32 v16, 0xb0, v148
	v_ashrrev_i32_e32 v17, 31, v16
	v_add_u32_e32 v136, 0xffffc0b0, v148
	v_lshlrev_b64 v[18:19], 14, v[16:17]
	v_lshlrev_b64 v[26:27], 13, v[136:137]
	v_lshlrev_b64 v[16:17], 13, v[16:17]
	v_lshl_add_u64 v[18:19], s[56:57], 0, v[18:19]
	v_cmp_gt_i32_e64 s[12:13], s59, v148
	s_and_b64 vcc, exec, s[10:11]
	v_lshl_add_u64 v[18:19], v[150:151], 1, v[18:19]
	v_cndmask_b32_e64 v17, v27, v17, s[12:13]
	v_cndmask_b32_e64 v16, v26, v16, s[12:13]
	v_fmamk_f32 v20, v20, 0x3a000000, v166
	v_mul_f32_e32 v21, 0x4b800000, v20
	v_cmp_gt_f32_e64 s[14:15], s51, v20
	s_nop 1
	v_cndmask_b32_e64 v20, v20, v21, s[14:15]
	v_rsq_f32_e32 v20, v20
	s_nop 0
	v_mul_f32_e32 v21, 0x45800000, v20
	v_cndmask_b32_e64 v20, v20, v21, s[14:15]
	v_pk_mul_f32 v[14:15], v[14:15], v[20:21] op_sel_hi:[1,0]
	v_pk_mul_f32 v[12:13], v[12:13], v[20:21] op_sel_hi:[1,0]
	v_pk_mul_f32 v[10:11], v[10:11], v[20:21] op_sel_hi:[1,0]
	v_pk_mul_f32 v[8:9], v[8:9], v[20:21] op_sel_hi:[1,0]
	v_cvt_pk_bf16_f32 v22, v12, v13
	v_cvt_pk_bf16_f32 v23, v14, v15
	v_cvt_pk_bf16_f32 v24, v8, v9
	v_cvt_pk_bf16_f32 v25, v10, v11
	global_store_dwordx4 v[18:19], v[22:25], off
	s_cbranch_vccnz .LBB0_898
	v_mov_b32_e32 v21, s21
	v_mov_b32_e32 v22, s23
	v_cndmask_b32_e64 v21, v21, v22, s[12:13]
	v_lshlrev_b32_e32 v136, 2, v21
	v_lshl_add_u64 v[22:23], s[44:45], 0, v[136:137]
	v_lshl_add_u64 v[22:23], v[22:23], 0, v[16:17]
	v_lshl_add_u64 v[22:23], v[146:147], 2, v[22:23]
	global_store_dwordx4 v[22:23], v[12:15], off nt
	global_store_dwordx4 v[22:23], v[8:11], off offset:16 nt
